# seam 0: replace the cooperative-groups grid sync with the XCD-hierarchical barrier used at the other seams (on top of combine fix + rss hoist)
# speedup vs baseline: 1.0084x; 1.0084x over previous
; __device__ __forceinline__ void xcd_barrier(const XcdBarrier& b) {
;     asm volatile("s_waitcnt vmcnt(0)" ::: "memory");
;     __syncthreads();
;     if (threadIdx.x == 0) {
;         unsigned* bar = b.bar;
;         __builtin_amdgcn_s_waitcnt(0);
;         unsigned nloc = b.st[0], nx = b.st[1];
;         if (nloc == 0u) { xcd_barrier_complete(bar, b.x, nloc, nx); b.st[0] = nloc; b.st[1] = nx; }
.LBB0_111:
	s_cmp_gt_i32 s59, 1
	s_cselect_b64 s[4:5], -1, 0
	s_and_b64 s[0:1], s[0:1], s[4:5]
	s_andn2_b64 vcc, exec, s[0:1]
	s_cbranch_vccnz .LBB0_123
	s_nop 0
	s_nop 0
	s_nop 0
	s_nop 0
	s_nop 0
	s_nop 0
	s_nop 0
	s_nop 0
	s_waitcnt vmcnt(0)
	s_waitcnt lgkmcnt(0)
	s_barrier
	s_mov_b64 s[0:1], exec
	v_readlane_b32 s6, v255, 4
	v_readlane_b32 s7, v255, 5
	s_and_b64 s[6:7], s[0:1], s[6:7]
	s_mov_b64 exec, s[6:7]
	s_cbranch_execz .Lmy_s0_266
	s_add_i32 s3, 0, 0x20040
	v_mov_b32_e32 v0, s3
	s_waitcnt vmcnt(0) expcnt(0) lgkmcnt(0)
	ds_read_b32 v2, v0
	s_add_i32 s3, 0, 0x20044
	v_mov_b32_e32 v0, s3
	ds_read_b32 v0, v0
	s_waitcnt lgkmcnt(1)
	v_cmp_ne_u32_e32 vcc, 0, v2
	s_cbranch_vccnz .Lmy_s0_230
	v_readlane_b32 s6, v255, 0
	v_readlane_b32 s7, v255, 1
	s_load_dwordx2 s[10:11], s[6:7], 0x4
	s_add_u32 s6, s54, 0x100200
	s_addc_u32 s7, s55, 0
	s_add_u32 s8, s54, 0x100400
	s_addc_u32 s9, s55, 0
	s_waitcnt lgkmcnt(0)
	s_mul_i32 s3, s10, s33
	s_add_u32 s10, s54, 0x100500
	s_mul_i32 s3, s3, s11
	s_addc_u32 s11, s55, 0
	s_add_u32 s12, s54, 0x100600
	s_addc_u32 s13, s55, 0
	s_add_u32 s36, s54, 0x100700
	s_addc_u32 s37, s55, 0
	s_add_u32 s38, s54, 0x100800
	s_addc_u32 s39, s55, 0
	s_add_u32 s40, s54, 0x100900
	s_addc_u32 s41, s55, 0
	s_add_u32 s42, s54, 0x100a00
	s_addc_u32 s43, s55, 0
	s_add_u32 s44, s54, 0x100b00
	s_addc_u32 s45, s55, 0
	s_add_u32 s64, s54, 0x100c00
	s_addc_u32 s65, s55, 0
	s_add_u32 s66, s54, 0x100d00
	s_addc_u32 s67, s55, 0
	s_add_u32 s68, s54, 0x100e00
	s_addc_u32 s69, s55, 0
	s_add_u32 s70, s54, 0x100f00
	s_addc_u32 s71, s55, 0
	s_add_u32 s72, s54, 0x101000
	s_addc_u32 s73, s55, 0
	s_add_u32 s74, s54, 0x101100
	s_addc_u32 s75, s55, 0
	s_add_u32 s76, s54, 0x101200
	s_addc_u32 s77, s55, 0
	s_add_u32 s78, s54, 0x101300
	s_addc_u32 s79, s55, 0
	s_mov_b32 s14, 1
	v_mov_b32_e32 v16, 0
	s_branch .Lmy_s0_218

;     __host__ __device__ bool next(int i, Unit& u) const {
;         const long L = (long)i * G + c; if (L >= nwg) return false;
;         int wgid = (int)L; { const int q = nwg / NXCD, r = nwg % NXCD, xcd = wgid % NXCD, off = wgid / NXCD; wgid = (xcd < r ? xcd * (q + 1) : r * (q + 1) + (xcd - r) * q) + off; }
;         const int nig = WGM * nN, gid = wgid / nig, fm = gid * WGM, gsz = (nM - fm) < WGM ? (nM - fm) : WGM;
;         u.pm = fm + ((wgid % nig) % gsz); u.pn = (wgid % nig) / gsz; return true;
; __device__ __forceinline__ void xcd_barrier(const XcdBarrier& b) {
;     ...
;     __syncthreads();
; }
.Lmy_s0_266:
	s_or_b64 exec, exec, s[0:1]
	s_waitcnt lgkmcnt(0)
	s_barrier
.LBB0_123:
	s_cmp_lt_i32 s58, 2
	s_cselect_b64 s[0:1], -1, 0
	s_add_u32 s24, s54, 0x2fc00000
	s_addc_u32 s25, s55, 0
	s_add_u32 s26, s54, 0x5400000
	s_addc_u32 s27, s55, 0
	s_add_u32 s28, s54, 0xf400000
	s_addc_u32 s29, s55, 0
	s_and_b64 s[0:1], s[0:1], s[4:5]
	s_andn2_b64 vcc, exec, s[0:1]
	s_cbranch_vccnz .LBB0_213
	v_mov_b32_e32 v8, v215
	s_cmpk_lt_i32 s2, 0xb40
	s_cselect_b64 s[4:5], -1, 0
	s_cmpk_gt_i32 s2, 0xb3f
	v_readfirstlane_b32 s6, v8
	s_cbranch_scc1 .LBB0_126
	s_ashr_i32 s3, s2, 31
	s_lshr_b32 s3, s3, 29
	s_add_i32 s3, s2, s3
	s_ashr_i32 s7, s3, 3
	s_and_b32 s3, s3, -8
	s_sub_i32 s3, s2, s3
	s_cmp_lt_i32 s3, 0
	s_movk_i32 s8, 0x169
	s_cselect_b32 s8, s8, 0x168
	s_mul_i32 s3, s3, s8
	s_add_i32 s3, s3, s7
	s_mul_hi_i32 s7, s3, 0x38e38e39
	s_lshr_b32 s8, s7, 31
	s_ashr_i32 s7, s7, 4
	s_add_i32 s7, s7, s8
	s_lshl_b32 s8, s7, 3
	s_mulk_i32 s7, 0x48
	s_sub_i32 s3, s3, s7
	s_bfe_i32 s7, s3, 0x80000
	s_bfe_u32 s7, s7, 0x3000c
	s_add_i32 s7, s3, s7
	s_bfe_i32 s9, s7, 0x80000
	s_and_b32 s7, s7, 0xf8
	s_sub_i32 s3, s3, s7
	s_sext_i32_i16 s9, s9
	s_sext_i32_i8 s3, s3
	s_add_i32 s36, s8, s3
	s_ashr_i32 s8, s9, 3
